# attention PV: V fragments via ds_read_b64 straight into MFMA operand registers (drops 32 v_mov per tile)
# speedup vs baseline: 1.0046x; 1.0046x over previous
; __device__ __forceinline__ void attn_unit(const Params& p, int b, int h, int q0, int nkeys, unsigned char* lds, int do_write) {
;     ...
; #pragma unroll
;         for (int mt = 0; mt < 4; ++mt)
; #pragma unroll
;             for (int kc = 0; kc < 2; ++kc) {
;                 union { uint2 h2[2]; bf16x8 v; } r;
;                 const unsigned char* vrow = Vs + (mt * 16 + fr) * 128 + (fq & 1) * 8;
;                 r.h2[0] = *(const uint2*)(vrow + (((4 * kc + (fq >> 1)) ^ kz) * 16));
;                 r.h2[1] = *(const uint2*)(vrow + (((4 * kc + 2 + (fq >> 1)) ^ kz) * 16));
; #pragma unroll
;                 for (int nq = 0; nq < 2; ++nq) oacc[mt][nq] = __builtin_amdgcn_mfma_f32_16x16x32_bf16(r.v, pf[kc][nq], oacc[mt][nq], 0, 0, 0);
;             }
;         if (!exact) {
; #pragma unroll
;             for (int nq = 0; nq < 2; ++nq) {
;                 const float alpha = __builtin_amdgcn_exp2f(-delta[nq]);
;                 lsum[nq] = (lsum[nq] + psum[nq]) * alpha;
; #pragma unroll
;                 for (int mt = 0; mt < 4; ++mt) oacc[mt][nq] = oacc[mt][nq] * alpha;
;             }
;         }
.LBB0_596:
	v_add3_u32 v70, s21, v108, v105
	v_add_u32_e32 v71, v70, v111
	v_add_u32_e32 v115, v70, v112
	v_add_u32_e32 v124, v70, v113
	v_add_u32_e32 v70, v70, v114
	s_waitcnt vmcnt(0)
	ds_read_b64 v[132:133], v71 offset:12288
	ds_read_b64 v[134:135], v115 offset:12288
	ds_read_b64 v[136:137], v71 offset:14336
	ds_read_b64 v[138:139], v115 offset:14336
	ds_read_b64 v[140:141], v124 offset:12288
	ds_read_b64 v[142:143], v70 offset:12288
	ds_read_b64 v[144:145], v124 offset:14336
	ds_read_b64 v[146:147], v70 offset:14336
	s_andn2_b64 vcc, exec, s[22:23]
	s_waitcnt lgkmcnt(6)
	v_mfma_f32_16x16x32_bf16 v[36:39], v[132:135], v[76:79], v[36:39]
	v_mfma_f32_16x16x32_bf16 v[24:27], v[132:135], v[60:63], v[24:27]
	ds_read_b64 v[148:149], v71 offset:16384
	ds_read_b64 v[150:151], v115 offset:16384
	s_waitcnt lgkmcnt(6)
	v_mfma_f32_16x16x32_bf16 v[40:43], v[136:139], v[76:79], v[40:43]
	v_mfma_f32_16x16x32_bf16 v[28:31], v[136:139], v[60:63], v[28:31]
	ds_read_b64 v[152:153], v124 offset:16384
	ds_read_b64 v[154:155], v70 offset:16384
	s_waitcnt lgkmcnt(6)
	v_mfma_f32_16x16x32_bf16 v[36:39], v[140:143], v[72:75], v[36:39]
	v_mfma_f32_16x16x32_bf16 v[24:27], v[140:143], v[56:59], v[24:27]
	ds_read_b64 v[156:157], v71 offset:18432
	ds_read_b64 v[158:159], v115 offset:18432
	s_waitcnt lgkmcnt(6)
	v_mfma_f32_16x16x32_bf16 v[40:43], v[144:147], v[72:75], v[40:43]
	v_mfma_f32_16x16x32_bf16 v[28:31], v[144:147], v[56:59], v[28:31]
	ds_read_b64 v[162:163], v124 offset:18432
	ds_read_b64 v[164:165], v70 offset:18432
	s_waitcnt lgkmcnt(6)
	v_mfma_f32_16x16x32_bf16 v[48:51], v[148:151], v[76:79], v[48:51]
	v_mfma_f32_16x16x32_bf16 v[32:35], v[148:151], v[60:63], v[32:35]
	s_waitcnt lgkmcnt(4)
	v_mfma_f32_16x16x32_bf16 v[48:51], v[152:155], v[72:75], v[48:51]
	v_mfma_f32_16x16x32_bf16 v[32:35], v[152:155], v[56:59], v[32:35]
	s_waitcnt lgkmcnt(2)
	v_mfma_f32_16x16x32_bf16 v[52:55], v[156:159], v[76:79], v[52:55]
	v_mfma_f32_16x16x32_bf16 v[44:47], v[156:159], v[60:63], v[44:47]
	s_waitcnt lgkmcnt(0)
	v_mfma_f32_16x16x32_bf16 v[52:55], v[162:165], v[72:75], v[52:55]
	v_mfma_f32_16x16x32_bf16 v[44:47], v[162:165], v[56:59], v[44:47]
	s_cbranch_vccnz .LBB0_582
	v_exp_f32_e64 v56, -v100
	v_pk_add_f32 v[58:59], v[64:65], v[90:91]
	v_pk_mul_f32 v[38:39], v[56:57], v[38:39] op_sel_hi:[0,1]
	v_pk_mul_f32 v[36:37], v[56:57], v[36:37] op_sel_hi:[0,1]
	v_pk_mul_f32 v[42:43], v[56:57], v[42:43] op_sel_hi:[0,1]
	v_pk_mul_f32 v[40:41], v[56:57], v[40:41] op_sel_hi:[0,1]
	v_pk_mul_f32 v[50:51], v[56:57], v[50:51] op_sel_hi:[0,1]
	v_pk_mul_f32 v[48:49], v[56:57], v[48:49] op_sel_hi:[0,1]
	v_pk_mul_f32 v[54:55], v[56:57], v[54:55] op_sel_hi:[0,1]
	v_pk_mul_f32 v[52:53], v[56:57], v[52:53] op_sel_hi:[0,1]
	v_exp_f32_e64 v57, -v101
	s_nop 0
	v_pk_mul_f32 v[90:91], v[56:57], v[58:59]
	v_mov_b32_e32 v56, v57
	v_pk_mul_f32 v[26:27], v[56:57], v[26:27] op_sel_hi:[0,1]
	v_pk_mul_f32 v[24:25], v[56:57], v[24:25] op_sel_hi:[0,1]
	v_pk_mul_f32 v[30:31], v[56:57], v[30:31] op_sel_hi:[0,1]
	v_pk_mul_f32 v[28:29], v[56:57], v[28:29] op_sel_hi:[0,1]
	v_pk_mul_f32 v[34:35], v[56:57], v[34:35] op_sel_hi:[0,1]
	v_pk_mul_f32 v[32:33], v[56:57], v[32:33] op_sel_hi:[0,1]
	v_pk_mul_f32 v[46:47], v[56:57], v[46:47] op_sel_hi:[0,1]
	v_pk_mul_f32 v[44:45], v[56:57], v[44:45] op_sel_hi:[0,1]
	s_branch .LBB0_582
